# grid barrier: per-XCD relay atomic dropped from the XCD leader path (nobody polls it after the release flattening)
# baseline (speedup 1.0000x reference)
; __device__ __forceinline__ unsigned xb_ld(unsigned* p)              { return __hip_atomic_load(p, __ATOMIC_RELAXED, __HIP_MEMORY_SCOPE_AGENT); }
; __device__ __forceinline__ unsigned xb_add(unsigned* p, unsigned v) { return __hip_atomic_fetch_add(p, v, __ATOMIC_RELAXED, __HIP_MEMORY_SCOPE_AGENT); }
; #define XB_SPIN(cond, bar) do { unsigned _sp = 0; while (cond) { __builtin_amdgcn_s_sleep(1); \
;     if ((++_sp & 255u) == 0u) { if (xb_ld(&(bar)[XB_TMO])) break; if (_sp > XB_SPIN_CAP) { atomicAdd(&(bar)[XB_TMO], 1u); break; } } } } while (0)
; __device__ __forceinline__ void xcd_barrier(const XcdBarrier& b, bool leader) {
;     ...
;             const unsigned og = xb_add(&bar[XB_TOP], 1u);
;             const unsigned tg = og / nx;
;             if (og + 1u == (tg + 1u) * nx) xb_add(&bar[XB_TOPGEN], 1u);
;             else XB_SPIN(xb_ld(&bar[XB_TOPGEN]) == tg, bar);
;             __builtin_amdgcn_fence(__ATOMIC_ACQUIRE, "agent");
;             xb_add(&bar[XB_XGEN(b.x)], 1u);
;             asm volatile("s_waitcnt vmcnt(0)" ::: "memory");
.LBB0_175:
	s_or_b64 exec, exec, s[8:9]
	s_mov_b64 s[8:9], exec
	v_mbcnt_lo_u32_b32 v0, s8, 0
	v_mbcnt_hi_u32_b32 v0, s9, v0
	v_cmp_eq_u32_e32 vcc, 0, v0
	s_waitcnt vmcnt(0)
	s_and_saveexec_b64 s[10:11], vcc
	s_cbranch_execz .LBB0_177
	s_bcnt1_i32_b64 s8, s[8:9]
	v_mov_b32_e32 v0, 0x2000
	v_mov_b32_e32 v1, s8
.LBB0_177:
	s_or_b64 exec, exec, s[10:11]
	s_waitcnt vmcnt(0)

; __device__ __forceinline__ unsigned xb_ld(unsigned* p)              { return __hip_atomic_load(p, __ATOMIC_RELAXED, __HIP_MEMORY_SCOPE_AGENT); }
; __device__ __forceinline__ unsigned xb_add(unsigned* p, unsigned v) { return __hip_atomic_fetch_add(p, v, __ATOMIC_RELAXED, __HIP_MEMORY_SCOPE_AGENT); }
; #define XB_SPIN(cond, bar) do { unsigned _sp = 0; while (cond) { __builtin_amdgcn_s_sleep(1); \
;     if ((++_sp & 255u) == 0u) { if (xb_ld(&(bar)[XB_TMO])) break; if (_sp > XB_SPIN_CAP) { atomicAdd(&(bar)[XB_TMO], 1u); break; } } } } while (0)
; __device__ __forceinline__ void xcd_barrier(const XcdBarrier& b, bool leader) {
;     ...
;             const unsigned og = xb_add(&bar[XB_TOP], 1u);
;             const unsigned tg = og / nx;
;             if (og + 1u == (tg + 1u) * nx) xb_add(&bar[XB_TOPGEN], 1u);
;             else XB_SPIN(xb_ld(&bar[XB_TOPGEN]) == tg, bar);
;             __builtin_amdgcn_fence(__ATOMIC_ACQUIRE, "agent");
;             xb_add(&bar[XB_XGEN(b.x)], 1u);
;             asm volatile("s_waitcnt vmcnt(0)" ::: "memory");
.LBB0_394:
	s_or_b64 exec, exec, s[8:9]
	s_mov_b64 s[8:9], exec
	v_mbcnt_lo_u32_b32 v0, s8, 0
	v_mbcnt_hi_u32_b32 v0, s9, v0
	v_cmp_eq_u32_e32 vcc, 0, v0
	s_waitcnt vmcnt(0)
	s_and_saveexec_b64 s[10:11], vcc
	s_cbranch_execz .LBB0_396
	s_bcnt1_i32_b64 s8, s[8:9]
	v_mov_b32_e32 v0, 0x2000
	v_mov_b32_e32 v1, s8
.LBB0_396:
	s_or_b64 exec, exec, s[10:11]
	s_waitcnt vmcnt(0)

; __device__ __forceinline__ unsigned xb_ld(unsigned* p)              { return __hip_atomic_load(p, __ATOMIC_RELAXED, __HIP_MEMORY_SCOPE_AGENT); }
; __device__ __forceinline__ unsigned xb_add(unsigned* p, unsigned v) { return __hip_atomic_fetch_add(p, v, __ATOMIC_RELAXED, __HIP_MEMORY_SCOPE_AGENT); }
; #define XB_SPIN(cond, bar) do { unsigned _sp = 0; while (cond) { __builtin_amdgcn_s_sleep(1); \
;     if ((++_sp & 255u) == 0u) { if (xb_ld(&(bar)[XB_TMO])) break; if (_sp > XB_SPIN_CAP) { atomicAdd(&(bar)[XB_TMO], 1u); break; } } } } while (0)
; __device__ __forceinline__ void xcd_barrier(const XcdBarrier& b, bool leader) {
;     ...
;             const unsigned og = xb_add(&bar[XB_TOP], 1u);
;             const unsigned tg = og / nx;
;             if (og + 1u == (tg + 1u) * nx) xb_add(&bar[XB_TOPGEN], 1u);
;             else XB_SPIN(xb_ld(&bar[XB_TOPGEN]) == tg, bar);
;             __builtin_amdgcn_fence(__ATOMIC_ACQUIRE, "agent");
;             xb_add(&bar[XB_XGEN(b.x)], 1u);
;             asm volatile("s_waitcnt vmcnt(0)" ::: "memory");
.LBB0_453:
	s_or_b64 exec, exec, s[8:9]
	s_mov_b64 s[8:9], exec
	v_mbcnt_lo_u32_b32 v0, s8, 0
	v_mbcnt_hi_u32_b32 v0, s9, v0
	v_cmp_eq_u32_e32 vcc, 0, v0
	s_waitcnt vmcnt(0)
	s_and_saveexec_b64 s[10:11], vcc
	s_cbranch_execz .LBB0_455
	s_bcnt1_i32_b64 s8, s[8:9]
	v_mov_b32_e32 v0, 0x2000
	v_mov_b32_e32 v1, s8
.LBB0_455:
	s_or_b64 exec, exec, s[10:11]
	s_waitcnt vmcnt(0)

; __device__ __forceinline__ unsigned xb_ld(unsigned* p)              { return __hip_atomic_load(p, __ATOMIC_RELAXED, __HIP_MEMORY_SCOPE_AGENT); }
; __device__ __forceinline__ unsigned xb_add(unsigned* p, unsigned v) { return __hip_atomic_fetch_add(p, v, __ATOMIC_RELAXED, __HIP_MEMORY_SCOPE_AGENT); }
; #define XB_SPIN(cond, bar) do { unsigned _sp = 0; while (cond) { __builtin_amdgcn_s_sleep(1); \
;     if ((++_sp & 255u) == 0u) { if (xb_ld(&(bar)[XB_TMO])) break; if (_sp > XB_SPIN_CAP) { atomicAdd(&(bar)[XB_TMO], 1u); break; } } } } while (0)
; __device__ __forceinline__ void xcd_barrier(const XcdBarrier& b, bool leader) {
;     ...
;             const unsigned og = xb_add(&bar[XB_TOP], 1u);
;             const unsigned tg = og / nx;
;             if (og + 1u == (tg + 1u) * nx) xb_add(&bar[XB_TOPGEN], 1u);
;             else XB_SPIN(xb_ld(&bar[XB_TOPGEN]) == tg, bar);
;             __builtin_amdgcn_fence(__ATOMIC_ACQUIRE, "agent");
;             xb_add(&bar[XB_XGEN(b.x)], 1u);
;             asm volatile("s_waitcnt vmcnt(0)" ::: "memory");
.LBB0_547:
	s_or_b64 exec, exec, s[8:9]
	s_mov_b64 s[8:9], exec
	v_mbcnt_lo_u32_b32 v0, s8, 0
	v_mbcnt_hi_u32_b32 v0, s9, v0
	v_cmp_eq_u32_e32 vcc, 0, v0
	s_waitcnt vmcnt(0)
	s_and_saveexec_b64 s[10:11], vcc
	s_cbranch_execz .LBB0_549
	s_bcnt1_i32_b64 s8, s[8:9]
	v_mov_b32_e32 v0, 0x2000
	v_mov_b32_e32 v1, s8
.LBB0_549:
	s_or_b64 exec, exec, s[10:11]
	s_waitcnt vmcnt(0)

; __device__ __forceinline__ unsigned xb_ld(unsigned* p)              { return __hip_atomic_load(p, __ATOMIC_RELAXED, __HIP_MEMORY_SCOPE_AGENT); }
; __device__ __forceinline__ unsigned xb_add(unsigned* p, unsigned v) { return __hip_atomic_fetch_add(p, v, __ATOMIC_RELAXED, __HIP_MEMORY_SCOPE_AGENT); }
; #define XB_SPIN(cond, bar) do { unsigned _sp = 0; while (cond) { __builtin_amdgcn_s_sleep(1); \
;     if ((++_sp & 255u) == 0u) { if (xb_ld(&(bar)[XB_TMO])) break; if (_sp > XB_SPIN_CAP) { atomicAdd(&(bar)[XB_TMO], 1u); break; } } } } while (0)
; __device__ __forceinline__ void xcd_barrier(const XcdBarrier& b, bool leader) {
;     ...
;             const unsigned og = xb_add(&bar[XB_TOP], 1u);
;             const unsigned tg = og / nx;
;             if (og + 1u == (tg + 1u) * nx) xb_add(&bar[XB_TOPGEN], 1u);
;             else XB_SPIN(xb_ld(&bar[XB_TOPGEN]) == tg, bar);
;             __builtin_amdgcn_fence(__ATOMIC_ACQUIRE, "agent");
;             xb_add(&bar[XB_XGEN(b.x)], 1u);
;             asm volatile("s_waitcnt vmcnt(0)" ::: "memory");
.LBB0_667:
	s_or_b64 exec, exec, s[8:9]
	s_mov_b64 s[8:9], exec
	v_mbcnt_lo_u32_b32 v0, s8, 0
	v_mbcnt_hi_u32_b32 v0, s9, v0
	v_cmp_eq_u32_e32 vcc, 0, v0
	s_waitcnt vmcnt(0)
	s_and_saveexec_b64 s[10:11], vcc
	s_cbranch_execz .LBB0_669
	s_bcnt1_i32_b64 s8, s[8:9]
	v_mov_b32_e32 v0, 0x2000
	v_mov_b32_e32 v1, s8
.LBB0_669:
	s_or_b64 exec, exec, s[10:11]
	s_waitcnt vmcnt(0)

; __device__ __forceinline__ unsigned xb_ld(unsigned* p)              { return __hip_atomic_load(p, __ATOMIC_RELAXED, __HIP_MEMORY_SCOPE_AGENT); }
; __device__ __forceinline__ unsigned xb_add(unsigned* p, unsigned v) { return __hip_atomic_fetch_add(p, v, __ATOMIC_RELAXED, __HIP_MEMORY_SCOPE_AGENT); }
; #define XB_SPIN(cond, bar) do { unsigned _sp = 0; while (cond) { __builtin_amdgcn_s_sleep(1); \
;     if ((++_sp & 255u) == 0u) { if (xb_ld(&(bar)[XB_TMO])) break; if (_sp > XB_SPIN_CAP) { atomicAdd(&(bar)[XB_TMO], 1u); break; } } } } while (0)
; __device__ __forceinline__ void xcd_barrier(const XcdBarrier& b, bool leader) {
;     ...
;             const unsigned og = xb_add(&bar[XB_TOP], 1u);
;             const unsigned tg = og / nx;
;             if (og + 1u == (tg + 1u) * nx) xb_add(&bar[XB_TOPGEN], 1u);
;             else XB_SPIN(xb_ld(&bar[XB_TOPGEN]) == tg, bar);
;             __builtin_amdgcn_fence(__ATOMIC_ACQUIRE, "agent");
;             xb_add(&bar[XB_XGEN(b.x)], 1u);
;             asm volatile("s_waitcnt vmcnt(0)" ::: "memory");
.LBB0_721:
	s_or_b64 exec, exec, s[8:9]
	s_mov_b64 s[8:9], exec
	v_mbcnt_lo_u32_b32 v0, s8, 0
	v_mbcnt_hi_u32_b32 v0, s9, v0
	v_cmp_eq_u32_e32 vcc, 0, v0
	s_waitcnt vmcnt(0)
	s_and_saveexec_b64 s[10:11], vcc
	s_cbranch_execz .LBB0_723
	s_bcnt1_i32_b64 s8, s[8:9]
	v_mov_b32_e32 v0, 0x2000
	v_mov_b32_e32 v1, s8
.LBB0_723:
	s_or_b64 exec, exec, s[10:11]
	s_waitcnt vmcnt(0)

; __device__ __forceinline__ unsigned xb_ld(unsigned* p)              { return __hip_atomic_load(p, __ATOMIC_RELAXED, __HIP_MEMORY_SCOPE_AGENT); }
; __device__ __forceinline__ unsigned xb_add(unsigned* p, unsigned v) { return __hip_atomic_fetch_add(p, v, __ATOMIC_RELAXED, __HIP_MEMORY_SCOPE_AGENT); }
; #define XB_SPIN(cond, bar) do { unsigned _sp = 0; while (cond) { __builtin_amdgcn_s_sleep(1); \
;     if ((++_sp & 255u) == 0u) { if (xb_ld(&(bar)[XB_TMO])) break; if (_sp > XB_SPIN_CAP) { atomicAdd(&(bar)[XB_TMO], 1u); break; } } } } while (0)
; __device__ __forceinline__ void xcd_barrier(const XcdBarrier& b, bool leader) {
;     ...
;             const unsigned og = xb_add(&bar[XB_TOP], 1u);
;             const unsigned tg = og / nx;
;             if (og + 1u == (tg + 1u) * nx) xb_add(&bar[XB_TOPGEN], 1u);
;             else XB_SPIN(xb_ld(&bar[XB_TOPGEN]) == tg, bar);
;             __builtin_amdgcn_fence(__ATOMIC_ACQUIRE, "agent");
;             xb_add(&bar[XB_XGEN(b.x)], 1u);
;             asm volatile("s_waitcnt vmcnt(0)" ::: "memory");
.LBB0_1019:
	s_or_b64 exec, exec, s[8:9]
	s_mov_b64 s[8:9], exec
	v_mbcnt_lo_u32_b32 v0, s8, 0
	v_mbcnt_hi_u32_b32 v0, s9, v0
	v_cmp_eq_u32_e32 vcc, 0, v0
	s_waitcnt vmcnt(0)
	s_and_saveexec_b64 s[10:11], vcc
	s_cbranch_execz .LBB0_1021
	s_bcnt1_i32_b64 s8, s[8:9]
	v_mov_b32_e32 v0, 0x2000
	v_mov_b32_e32 v1, s8
.LBB0_1021:
	s_or_b64 exec, exec, s[10:11]
	s_waitcnt vmcnt(0)

; __device__ __forceinline__ unsigned xb_ld(unsigned* p)              { return __hip_atomic_load(p, __ATOMIC_RELAXED, __HIP_MEMORY_SCOPE_AGENT); }
; __device__ __forceinline__ unsigned xb_add(unsigned* p, unsigned v) { return __hip_atomic_fetch_add(p, v, __ATOMIC_RELAXED, __HIP_MEMORY_SCOPE_AGENT); }
; #define XB_SPIN(cond, bar) do { unsigned _sp = 0; while (cond) { __builtin_amdgcn_s_sleep(1); \
;     if ((++_sp & 255u) == 0u) { if (xb_ld(&(bar)[XB_TMO])) break; if (_sp > XB_SPIN_CAP) { atomicAdd(&(bar)[XB_TMO], 1u); break; } } } } while (0)
; __device__ __forceinline__ void xcd_barrier(const XcdBarrier& b, bool leader) {
;     ...
;             const unsigned og = xb_add(&bar[XB_TOP], 1u);
;             const unsigned tg = og / nx;
;             if (og + 1u == (tg + 1u) * nx) xb_add(&bar[XB_TOPGEN], 1u);
;             else XB_SPIN(xb_ld(&bar[XB_TOPGEN]) == tg, bar);
;             __builtin_amdgcn_fence(__ATOMIC_ACQUIRE, "agent");
;             xb_add(&bar[XB_XGEN(b.x)], 1u);
;             asm volatile("s_waitcnt vmcnt(0)" ::: "memory");
.LBB0_1463:
	s_or_b64 exec, exec, s[8:9]
	s_mov_b64 s[8:9], exec
	v_mbcnt_lo_u32_b32 v0, s8, 0
	v_mbcnt_hi_u32_b32 v0, s9, v0
	v_cmp_eq_u32_e32 vcc, 0, v0
	s_waitcnt vmcnt(0)
	s_and_saveexec_b64 s[10:11], vcc
	s_cbranch_execz .LBB0_1465
	s_bcnt1_i32_b64 s3, s[8:9]
	v_mov_b32_e32 v0, 0x2000
	v_mov_b32_e32 v1, s3
.LBB0_1465:
	s_or_b64 exec, exec, s[10:11]
	s_waitcnt vmcnt(0)

; __device__ __forceinline__ unsigned xb_ld(unsigned* p)              { return __hip_atomic_load(p, __ATOMIC_RELAXED, __HIP_MEMORY_SCOPE_AGENT); }
; __device__ __forceinline__ unsigned xb_add(unsigned* p, unsigned v) { return __hip_atomic_fetch_add(p, v, __ATOMIC_RELAXED, __HIP_MEMORY_SCOPE_AGENT); }
; #define XB_SPIN(cond, bar) do { unsigned _sp = 0; while (cond) { __builtin_amdgcn_s_sleep(1); \
;     if ((++_sp & 255u) == 0u) { if (xb_ld(&(bar)[XB_TMO])) break; if (_sp > XB_SPIN_CAP) { atomicAdd(&(bar)[XB_TMO], 1u); break; } } } } while (0)
; __device__ __forceinline__ void xcd_barrier(const XcdBarrier& b, bool leader) {
;     ...
;             const unsigned og = xb_add(&bar[XB_TOP], 1u);
;             const unsigned tg = og / nx;
;             if (og + 1u == (tg + 1u) * nx) xb_add(&bar[XB_TOPGEN], 1u);
;             else XB_SPIN(xb_ld(&bar[XB_TOPGEN]) == tg, bar);
;             __builtin_amdgcn_fence(__ATOMIC_ACQUIRE, "agent");
;             xb_add(&bar[XB_XGEN(b.x)], 1u);
;             asm volatile("s_waitcnt vmcnt(0)" ::: "memory");
.LBB0_1887:
	s_or_b64 exec, exec, s[8:9]
	s_mov_b64 s[8:9], exec
	v_mbcnt_lo_u32_b32 v0, s8, 0
	v_mbcnt_hi_u32_b32 v0, s9, v0
	v_cmp_eq_u32_e32 vcc, 0, v0
	s_waitcnt vmcnt(0)
	s_and_saveexec_b64 s[10:11], vcc
	s_cbranch_execz .LBB0_1889
	s_bcnt1_i32_b64 s3, s[8:9]
	v_mov_b32_e32 v0, 0x2000
	v_mov_b32_e32 v1, s3
.LBB0_1889:
	s_or_b64 exec, exec, s[10:11]
	s_waitcnt vmcnt(0)

; __device__ __forceinline__ unsigned xb_ld(unsigned* p)              { return __hip_atomic_load(p, __ATOMIC_RELAXED, __HIP_MEMORY_SCOPE_AGENT); }
; __device__ __forceinline__ unsigned xb_add(unsigned* p, unsigned v) { return __hip_atomic_fetch_add(p, v, __ATOMIC_RELAXED, __HIP_MEMORY_SCOPE_AGENT); }
; #define XB_SPIN(cond, bar) do { unsigned _sp = 0; while (cond) { __builtin_amdgcn_s_sleep(1); \
;     if ((++_sp & 255u) == 0u) { if (xb_ld(&(bar)[XB_TMO])) break; if (_sp > XB_SPIN_CAP) { atomicAdd(&(bar)[XB_TMO], 1u); break; } } } } while (0)
; __device__ __forceinline__ void xcd_barrier(const XcdBarrier& b, bool leader) {
;     ...
;             const unsigned og = xb_add(&bar[XB_TOP], 1u);
;             const unsigned tg = og / nx;
;             if (og + 1u == (tg + 1u) * nx) xb_add(&bar[XB_TOPGEN], 1u);
;             else XB_SPIN(xb_ld(&bar[XB_TOPGEN]) == tg, bar);
;             __builtin_amdgcn_fence(__ATOMIC_ACQUIRE, "agent");
;             xb_add(&bar[XB_XGEN(b.x)], 1u);
;             asm volatile("s_waitcnt vmcnt(0)" ::: "memory");
.LBB0_1992:
	s_or_b64 exec, exec, s[8:9]
	s_mov_b64 s[8:9], exec
	v_mbcnt_lo_u32_b32 v0, s8, 0
	v_mbcnt_hi_u32_b32 v0, s9, v0
	v_cmp_eq_u32_e32 vcc, 0, v0
	s_waitcnt vmcnt(0)
	s_and_saveexec_b64 s[10:11], vcc
	s_cbranch_execz .LBB0_1994
	s_bcnt1_i32_b64 s3, s[8:9]
	v_mov_b32_e32 v0, 0x2000
	v_mov_b32_e32 v1, s3
.LBB0_1994:
	s_or_b64 exec, exec, s[10:11]
	s_waitcnt vmcnt(0)

; __device__ __forceinline__ unsigned xb_ld(unsigned* p)              { return __hip_atomic_load(p, __ATOMIC_RELAXED, __HIP_MEMORY_SCOPE_AGENT); }
; __device__ __forceinline__ unsigned xb_add(unsigned* p, unsigned v) { return __hip_atomic_fetch_add(p, v, __ATOMIC_RELAXED, __HIP_MEMORY_SCOPE_AGENT); }
; #define XB_SPIN(cond, bar) do { unsigned _sp = 0; while (cond) { __builtin_amdgcn_s_sleep(1); \
;     if ((++_sp & 255u) == 0u) { if (xb_ld(&(bar)[XB_TMO])) break; if (_sp > XB_SPIN_CAP) { atomicAdd(&(bar)[XB_TMO], 1u); break; } } } } while (0)
; __device__ __forceinline__ void xcd_barrier(const XcdBarrier& b, bool leader) {
;     ...
;             const unsigned og = xb_add(&bar[XB_TOP], 1u);
;             const unsigned tg = og / nx;
;             if (og + 1u == (tg + 1u) * nx) xb_add(&bar[XB_TOPGEN], 1u);
;             else XB_SPIN(xb_ld(&bar[XB_TOPGEN]) == tg, bar);
;             __builtin_amdgcn_fence(__ATOMIC_ACQUIRE, "agent");
;             xb_add(&bar[XB_XGEN(b.x)], 1u);
;             asm volatile("s_waitcnt vmcnt(0)" ::: "memory");
.LBB0_2098:
	s_or_b64 exec, exec, s[8:9]
	s_mov_b64 s[8:9], exec
	v_mbcnt_lo_u32_b32 v0, s8, 0
	v_mbcnt_hi_u32_b32 v0, s9, v0
	v_cmp_eq_u32_e32 vcc, 0, v0
	s_waitcnt vmcnt(0)
	s_and_saveexec_b64 s[10:11], vcc
	s_cbranch_execz .LBB0_2100
	s_bcnt1_i32_b64 s3, s[8:9]
	v_mov_b32_e32 v0, 0x2000
	v_mov_b32_e32 v1, s3
.LBB0_2100:
	s_or_b64 exec, exec, s[10:11]
	s_waitcnt vmcnt(0)

; __device__ __forceinline__ unsigned xb_ld(unsigned* p)              { return __hip_atomic_load(p, __ATOMIC_RELAXED, __HIP_MEMORY_SCOPE_AGENT); }
; __device__ __forceinline__ unsigned xb_add(unsigned* p, unsigned v) { return __hip_atomic_fetch_add(p, v, __ATOMIC_RELAXED, __HIP_MEMORY_SCOPE_AGENT); }
; #define XB_SPIN(cond, bar) do { unsigned _sp = 0; while (cond) { __builtin_amdgcn_s_sleep(1); \
;     if ((++_sp & 255u) == 0u) { if (xb_ld(&(bar)[XB_TMO])) break; if (_sp > XB_SPIN_CAP) { atomicAdd(&(bar)[XB_TMO], 1u); break; } } } } while (0)
; __device__ __forceinline__ void xcd_barrier(const XcdBarrier& b, bool leader) {
;     ...
;             const unsigned og = xb_add(&bar[XB_TOP], 1u);
;             const unsigned tg = og / nx;
;             if (og + 1u == (tg + 1u) * nx) xb_add(&bar[XB_TOPGEN], 1u);
;             else XB_SPIN(xb_ld(&bar[XB_TOPGEN]) == tg, bar);
;             __builtin_amdgcn_fence(__ATOMIC_ACQUIRE, "agent");
;             xb_add(&bar[XB_XGEN(b.x)], 1u);
;             asm volatile("s_waitcnt vmcnt(0)" ::: "memory");
.LBB0_2181:
	s_or_b64 exec, exec, s[10:11]
	s_mov_b64 s[10:11], exec
	v_mbcnt_lo_u32_b32 v0, s10, 0
	v_mbcnt_hi_u32_b32 v0, s11, v0
	v_cmp_eq_u32_e32 vcc, 0, v0
	s_waitcnt vmcnt(0)
	s_and_saveexec_b64 s[12:13], vcc
	s_cbranch_execz .LBB0_2183
	s_bcnt1_i32_b64 s3, s[10:11]
	v_mov_b32_e32 v0, 0x2000
	v_mov_b32_e32 v1, s3
.LBB0_2183:
	s_or_b64 exec, exec, s[12:13]
	s_waitcnt vmcnt(0)

; __device__ __forceinline__ unsigned xb_ld(unsigned* p)              { return __hip_atomic_load(p, __ATOMIC_RELAXED, __HIP_MEMORY_SCOPE_AGENT); }
; __device__ __forceinline__ unsigned xb_add(unsigned* p, unsigned v) { return __hip_atomic_fetch_add(p, v, __ATOMIC_RELAXED, __HIP_MEMORY_SCOPE_AGENT); }
; #define XB_SPIN(cond, bar) do { unsigned _sp = 0; while (cond) { __builtin_amdgcn_s_sleep(1); \
;     if ((++_sp & 255u) == 0u) { if (xb_ld(&(bar)[XB_TMO])) break; if (_sp > XB_SPIN_CAP) { atomicAdd(&(bar)[XB_TMO], 1u); break; } } } } while (0)
; __device__ __forceinline__ void xcd_barrier(const XcdBarrier& b, bool leader) {
;     ...
;             const unsigned og = xb_add(&bar[XB_TOP], 1u);
;             const unsigned tg = og / nx;
;             if (og + 1u == (tg + 1u) * nx) xb_add(&bar[XB_TOPGEN], 1u);
;             else XB_SPIN(xb_ld(&bar[XB_TOPGEN]) == tg, bar);
;             __builtin_amdgcn_fence(__ATOMIC_ACQUIRE, "agent");
;             xb_add(&bar[XB_XGEN(b.x)], 1u);
;             asm volatile("s_waitcnt vmcnt(0)" ::: "memory");
.LBB0_2297:
	s_or_b64 exec, exec, s[10:11]
	s_mov_b64 s[10:11], exec
	v_mbcnt_lo_u32_b32 v0, s10, 0
	v_mbcnt_hi_u32_b32 v0, s11, v0
	v_cmp_eq_u32_e32 vcc, 0, v0
	s_waitcnt vmcnt(0)
	s_and_saveexec_b64 s[12:13], vcc
	s_cbranch_execz .LBB0_2299
	s_bcnt1_i32_b64 s3, s[10:11]
	v_mov_b32_e32 v0, 0x2000
	v_mov_b32_e32 v1, s3
.LBB0_2299:
	s_or_b64 exec, exec, s[12:13]
	s_waitcnt vmcnt(0)

; __device__ __forceinline__ unsigned xb_ld(unsigned* p)              { return __hip_atomic_load(p, __ATOMIC_RELAXED, __HIP_MEMORY_SCOPE_AGENT); }
; __device__ __forceinline__ unsigned xb_add(unsigned* p, unsigned v) { return __hip_atomic_fetch_add(p, v, __ATOMIC_RELAXED, __HIP_MEMORY_SCOPE_AGENT); }
; #define XB_SPIN(cond, bar) do { unsigned _sp = 0; while (cond) { __builtin_amdgcn_s_sleep(1); \
;     if ((++_sp & 255u) == 0u) { if (xb_ld(&(bar)[XB_TMO])) break; if (_sp > XB_SPIN_CAP) { atomicAdd(&(bar)[XB_TMO], 1u); break; } } } } while (0)
; __device__ __forceinline__ void xcd_barrier(const XcdBarrier& b, bool leader) {
;     ...
;             const unsigned og = xb_add(&bar[XB_TOP], 1u);
;             const unsigned tg = og / nx;
;             if (og + 1u == (tg + 1u) * nx) xb_add(&bar[XB_TOPGEN], 1u);
;             else XB_SPIN(xb_ld(&bar[XB_TOPGEN]) == tg, bar);
;             __builtin_amdgcn_fence(__ATOMIC_ACQUIRE, "agent");
;             xb_add(&bar[XB_XGEN(b.x)], 1u);
;             asm volatile("s_waitcnt vmcnt(0)" ::: "memory");
.LBB0_2417:
	s_or_b64 exec, exec, s[6:7]
	s_mov_b64 s[6:7], exec
	v_mbcnt_lo_u32_b32 v0, s6, 0
	v_mbcnt_hi_u32_b32 v0, s7, v0
	v_cmp_eq_u32_e32 vcc, 0, v0
	s_waitcnt vmcnt(0)
	s_and_saveexec_b64 s[10:11], vcc
	s_cbranch_execz .LBB0_2419
	s_bcnt1_i32_b64 s6, s[6:7]
	v_mov_b32_e32 v0, 0x2000
	v_mov_b32_e32 v1, s6
.LBB0_2419:
	s_or_b64 exec, exec, s[10:11]
	s_waitcnt vmcnt(0)
